# GEMM phase prologue de-serialised: second batch of stage loads (buffer 1) issued before the first counted wait+barrier instead of after it
# speedup vs baseline: 1.0201x; 1.0003x over previous
; #define PG8_STAGE(bufoff, gbase, voff) do { _Pragma("unroll") for (int _i = 0; _i < 2; ++_i) \
;         __builtin_amdgcn_global_load_lds((const unsigned*)((const char*)(gbase) + (voff)[_i]), (LAS unsigned*)(lds + (bufoff) + ldsw + _i * 8192), 16, 0, 0); } while (0)
; #define PG8_WAIT_V(n) asm volatile("s_waitcnt vmcnt(" #n ")" ::: "memory")
; #define PG8_BAR __builtin_amdgcn_s_barrier()
; template <class Epi>
; __device__ __forceinline__ void gemm_phase(LAS unsigned char* lds, const Gemm g, const StaticOrder& S, const Epi& E) {
;     ...
;     for (int i = 0; i < 2; ++i) { int R, C; stage_rc(tid * 16 + i * 8192, R, C); const int Rb = (R & ~31) + perm32(R & 31);
;         voffA[i] = (unsigned)(R * K + C) * 2u; voffB[i] = (unsigned)(Rb * K + C) * 2u; }
;     const size_t kstep = (size_t)(BK * 2);
;     const size_t hstep = (size_t)HALF * K * 2;
;     const size_t tstep = 2 * hstep;
;     const unsigned ldsw = (unsigned)wid * 1024u;
;     const int aoff = lds_byte(wr * 64 + fr, fq * 8), boff = lds_byte(wc * 32 + fr, fq * 8);
;     ...
;     PG8_STAGE(PG8_SB(0, 0), cB, voffB); PG8_STAGE(PG8_SA(0, 0), cA, voffA); PG8_STAGE(PG8_SB(0, 1), cB + hstep, voffB); PG8_STAGE(PG8_SA(0, 1), cA + hstep, voffA);
;     if (wr == 1) PG8_BAR;
;     PG8_WAIT_V(4); PG8_BAR;
;     PG8_STAGE(PG8_SB(1, 0), cB + kstep, voffB); PG8_STAGE(PG8_SA(1, 0), cA + kstep, voffA); PG8_STAGE(PG8_SB(1, 1), cB + hstep + kstep, voffB);
;     PG8_WAIT_V(6); PG8_BAR;
.LBB0_60:
	s_and_b64 s[36:37], s[36:37], exec
	v_readlane_b32 s36, v251, 58
	s_sext_i32_i16 s80, s44
	v_readlane_b32 s37, v251, 59
	v_readlane_b32 s44, v251, 63
	v_bfe_u32 v18, v12, 4, 2
	s_cselect_b32 s45, s37, s44
	v_readlane_b32 s37, v251, 62
	v_and_b32_e32 v141, 15, v12
	v_lshlrev_b32_e32 v19, 4, v18
	v_lshlrev_b32_e32 v20, 2, v12
	s_cselect_b32 s44, s36, s37
	v_lshl_or_b32 v19, v141, 6, v19
	s_lshl_b32 s36, s46, 13
	v_and_b32_e32 v20, 32, v20
	v_bitop3_b32 v21, v19, s36, v20 bitop3:0xde
	s_lshl_b32 s36, s43, 5
	s_lshl_b32 s75, s46, 6
	s_and_b32 s46, s36, 0x60
	s_add_i32 m0, s55, 0x18000
	v_lshl_add_u64 v[8:9], v[8:9], 0, s[22:23]
	s_lshl_b32 s36, s46, 7
	global_load_lds_dwordx4 v[8:9], off
	v_lshl_add_u64 v[6:7], v[6:7], 0, s[22:23]
	s_add_i32 m0, s55, 0x1a000
	s_add_i32 s76, s55, 0x8000
	s_add_i32 s77, s55, 0xa000
	v_bitop3_b32 v143, v19, s36, v20 bitop3:0xde
	global_load_lds_dwordx4 v[6:7], off
	v_lshl_add_u64 v[4:5], v[4:5], 0, s[22:23]
	s_mov_b32 m0, s76
	s_add_u32 s36, s58, 0x80080
	global_load_lds_dwordx4 v[4:5], off
	v_lshl_add_u64 v[2:3], v[2:3], 0, s[22:23]
	s_mov_b32 m0, s77
	s_addc_u32 s37, s59, 0
	global_load_lds_dwordx4 v[2:3], off
	s_add_i32 m0, s55, 0x1c000
	v_lshl_add_u64 v[2:3], s[36:37], 0, v[0:1]
	global_load_lds_dwordx4 v[2:3], off
	v_lshl_add_u64 v[2:3], s[36:37], 0, v[130:131]
	s_add_i32 m0, s55, 0x1e000
	v_readlane_b32 s36, v254, 38
	global_load_lds_dwordx4 v[2:3], off
	s_waitcnt vmcnt(10)
	s_barrier
	v_mul_f32_e32 v2, 0x4f7ffffe, v17
	v_cvt_u32_f32_e32 v2, v2
	v_readlane_b32 s37, v254, 39
	v_and_b32_e32 v3, 1, v15
	s_mov_b32 s43, s36
	v_readfirstlane_b32 s37, v2
	v_lshlrev_b32_e32 v2, 15, v15
	v_and_b32_e32 v2, 0xffff0000, v2
	v_lshl_add_u32 v2, v14, 12, v2
	v_lshl_or_b32 v2, v3, 6, v2
	v_lshl_add_u32 v136, v16, 1, v2
	v_lshlrev_b32_e32 v2, 15, v10
	v_and_b32_e32 v2, 0xffff0000, v2
	s_sub_i32 s36, 0, s70
	v_lshl_add_u32 v2, v11, 12, v2
	v_and_b32_e32 v3, 1, v10
	s_waitcnt vmcnt(6)
	s_mul_i32 s36, s36, s37
	v_lshl_or_b32 v2, v3, 6, v2
	v_and_b32_e32 v145, 63, v12
	s_mul_hi_u32 s36, s37, s36
	v_lshl_add_u32 v138, v13, 1, v2
	v_and_or_b32 v2, v234, 64, v141
	v_or_b32_e32 v147, 0x80, v145
	v_lshl_or_b32 v149, v18, 3, s46
	s_mov_b32 s78, 0
	s_add_i32 s79, s37, s36
	v_mov_b32_e32 v137, v1
	v_mov_b32_e32 v139, v1
	v_add_u32_e32 v151, 0, v21
	v_lshlrev_b32_e32 v152, 2, v2
	s_barrier

; #define PG8_STAGE(bufoff, gbase, voff) do { _Pragma("unroll") for (int _i = 0; _i < 2; ++_i) \
;         __builtin_amdgcn_global_load_lds((const unsigned*)((const char*)(gbase) + (voff)[_i]), (LAS unsigned*)(lds + (bufoff) + ldsw + _i * 8192), 16, 0, 0); } while (0)
; #define PG8_WAIT_V(n) asm volatile("s_waitcnt vmcnt(" #n ")" ::: "memory")
; #define PG8_BAR __builtin_amdgcn_s_barrier()
; template <class Epi>
; __device__ __forceinline__ void gemm_phase(LAS unsigned char* lds, const Gemm g, const StaticOrder& S, const Epi& E) {
;     ...
;     for (int i = 0; i < 2; ++i) { int R, C; stage_rc(tid * 16 + i * 8192, R, C); const int Rb = (R & ~31) + perm32(R & 31);
;         voffA[i] = (unsigned)(R * K + C) * 2u; voffB[i] = (unsigned)(Rb * K + C) * 2u; }
;     const size_t kstep = (size_t)(BK * 2);
;     const size_t hstep = (size_t)HALF * K * 2;
;     const size_t tstep = 2 * hstep;
;     const unsigned ldsw = (unsigned)wid * 1024u;
;     const int aoff = lds_byte(wr * 64 + fr, fq * 8), boff = lds_byte(wc * 32 + fr, fq * 8);
;     ...
;     PG8_STAGE(PG8_SB(0, 0), cB, voffB); PG8_STAGE(PG8_SA(0, 0), cA, voffA); PG8_STAGE(PG8_SB(0, 1), cB + hstep, voffB); PG8_STAGE(PG8_SA(0, 1), cA + hstep, voffA);
;     if (wr == 1) PG8_BAR;
;     PG8_WAIT_V(4); PG8_BAR;
;     PG8_STAGE(PG8_SB(1, 0), cB + kstep, voffB); PG8_STAGE(PG8_SA(1, 0), cA + kstep, voffA); PG8_STAGE(PG8_SB(1, 1), cB + hstep + kstep, voffB);
;     PG8_WAIT_V(6); PG8_BAR;
.LBB0_73:
	v_readlane_b32 s42, v254, 44
	v_readlane_b32 s43, v254, 45
	s_lshl_b64 s[42:43], s[42:43], 19
	v_readlane_b32 s46, v252, 2
	s_add_u32 s42, s46, s42
	v_readlane_b32 s46, v252, 3
	s_addc_u32 s43, s46, s43
	v_bfe_u32 v18, v16, 4, 2
	s_lshl_b32 s44, s44, 5
	v_and_b32_e32 v17, 15, v16
	v_lshlrev_b32_e32 v19, 4, v18
	v_lshlrev_b32_e32 v16, 2, v16
	s_and_b32 s46, s44, 0x60
	s_add_i32 m0, s65, 0x18000
	v_lshl_add_u64 v[8:9], v[8:9], 0, s[22:23]
	v_lshl_or_b32 v140, s45, 6, v17
	v_lshl_or_b32 v17, v17, 6, v19
	s_lshl_b32 s45, s45, 13
	v_and_b32_e32 v16, 32, v16
	s_lshl_b32 s44, s46, 7
	global_load_lds_dwordx4 v[8:9], off
	v_lshl_add_u64 v[6:7], v[6:7], 0, s[22:23]
	s_add_i32 m0, s65, 0x1a000
	s_add_i32 s71, s65, 0x8000
	s_add_i32 s72, s65, 0xa000
	v_bitop3_b32 v141, v17, s44, v16 bitop3:0xde
	global_load_lds_dwordx4 v[6:7], off
	v_lshl_add_u64 v[4:5], v[4:5], 0, s[22:23]
	s_mov_b32 m0, s71
	s_add_u32 s44, s56, 0x80080
	v_bitop3_b32 v19, v17, s45, v16 bitop3:0xde
	global_load_lds_dwordx4 v[4:5], off
	v_lshl_add_u64 v[2:3], v[2:3], 0, s[22:23]
	s_mov_b32 m0, s72
	s_addc_u32 s45, s57, 0
	global_load_lds_dwordx4 v[2:3], off
	s_add_i32 m0, s65, 0x1c000
	v_lshl_add_u64 v[2:3], s[44:45], 0, v[0:1]
	global_load_lds_dwordx4 v[2:3], off
	v_lshl_add_u64 v[2:3], s[44:45], 0, v[130:131]
	s_add_i32 m0, s65, 0x1e000
	v_lshl_or_b32 v142, v18, 3, s46
	global_load_lds_dwordx4 v[2:3], off
	s_waitcnt vmcnt(10)
	s_barrier
	v_lshlrev_b32_e32 v2, 15, v14
	v_and_b32_e32 v2, 0xffff0000, v2
	v_lshl_add_u32 v2, v13, 12, v2
	v_and_b32_e32 v3, 1, v14
	v_lshl_or_b32 v2, v3, 6, v2
	v_lshl_add_u32 v136, v15, 1, v2
	v_lshlrev_b32_e32 v2, 15, v10
	v_and_b32_e32 v2, 0xffff0000, v2
	s_waitcnt vmcnt(6)
	v_lshl_add_u32 v2, v11, 12, v2
	v_and_b32_e32 v3, 1, v10
	v_lshl_or_b32 v2, v3, 6, v2
	v_mov_b32_e32 v137, v1
	v_lshl_add_u32 v138, v12, 1, v2
	v_mov_b32_e32 v139, v1
	s_mov_b32 s74, 0
	v_add_u32_e32 v143, 0, v19
	v_readlane_b32 s75, v252, 16
	s_mov_b64 s[54:55], s[36:37]
	s_mov_b32 s73, 0
	s_barrier
	s_waitcnt vmcnt(0)

; #define PG8_STAGE(bufoff, gbase, voff) do { _Pragma("unroll") for (int _i = 0; _i < 2; ++_i) \
;         __builtin_amdgcn_global_load_lds((const unsigned*)((const char*)(gbase) + (voff)[_i]), (LAS unsigned*)(lds + (bufoff) + ldsw + _i * 8192), 16, 0, 0); } while (0)
; #define PG8_WAIT_V(n) asm volatile("s_waitcnt vmcnt(" #n ")" ::: "memory")
; #define PG8_BAR __builtin_amdgcn_s_barrier()
; template <class Epi>
; __device__ __forceinline__ void gemm_phase(LAS unsigned char* lds, const Gemm g, const StaticOrder& S, const Epi& E) {
;     ...
;     for (int i = 0; i < 2; ++i) { int R, C; stage_rc(tid * 16 + i * 8192, R, C); const int Rb = (R & ~31) + perm32(R & 31);
;         voffA[i] = (unsigned)(R * K + C) * 2u; voffB[i] = (unsigned)(Rb * K + C) * 2u; }
;     const size_t kstep = (size_t)(BK * 2);
;     const size_t hstep = (size_t)HALF * K * 2;
;     const size_t tstep = 2 * hstep;
;     const unsigned ldsw = (unsigned)wid * 1024u;
;     const int aoff = lds_byte(wr * 64 + fr, fq * 8), boff = lds_byte(wc * 32 + fr, fq * 8);
;     ...
;     PG8_STAGE(PG8_SB(0, 0), cB, voffB); PG8_STAGE(PG8_SA(0, 0), cA, voffA); PG8_STAGE(PG8_SB(0, 1), cB + hstep, voffB); PG8_STAGE(PG8_SA(0, 1), cA + hstep, voffA);
;     if (wr == 1) PG8_BAR;
;     PG8_WAIT_V(4); PG8_BAR;
;     PG8_STAGE(PG8_SB(1, 0), cB + kstep, voffB); PG8_STAGE(PG8_SA(1, 0), cA + kstep, voffA); PG8_STAGE(PG8_SB(1, 1), cB + hstep + kstep, voffB);
;     PG8_WAIT_V(6); PG8_BAR;
.LBB0_86:
	v_readlane_b32 s46, v254, 12
	s_lshl_b32 s36, s36, 5
	v_mov_b32_e32 v135, v1
	v_readlane_b32 s47, v254, 13
	s_and_b32 s39, s36, 0x60
	s_add_i32 m0, s56, 0x18000
	v_lshl_add_u64 v[2:3], v[2:3], 0, s[22:23]
	v_lshl_add_u64 v[14:15], s[46:47], 0, v[134:135]
	v_mov_b32_e32 v133, v1
	s_lshl_b32 s60, s37, 6
	s_lshl_b32 s38, s37, 13
	s_lshl_b32 s40, s39, 7
	global_load_lds_dwordx4 v[2:3], off
	v_lshl_add_u64 v[2:3], v[4:5], 0, s[22:23]
	s_add_i32 m0, s56, 0x1a000
	s_add_i32 s61, s56, 0x8000
	s_add_i32 s63, s56, 0xa000
	v_lshl_add_u64 v[16:17], s[46:47], 0, v[132:133]
	global_load_lds_dwordx4 v[2:3], off
	v_lshl_add_u64 v[2:3], v[14:15], 0, s[22:23]
	s_mov_b32 m0, s61
	s_add_u32 s36, s48, 0x80080
	global_load_lds_dwordx4 v[2:3], off
	v_lshl_add_u64 v[2:3], v[16:17], 0, s[22:23]
	s_mov_b32 m0, s63
	s_addc_u32 s37, s49, 0
	global_load_lds_dwordx4 v[2:3], off
	s_add_i32 m0, s56, 0x1c000
	v_lshl_add_u64 v[2:3], s[36:37], 0, v[0:1]
	global_load_lds_dwordx4 v[2:3], off
	v_lshl_add_u64 v[2:3], s[36:37], 0, v[130:131]
	s_add_i32 m0, s56, 0x1e000
	v_and_b32_e32 v141, 15, v6
	global_load_lds_dwordx4 v[2:3], off
	s_waitcnt vmcnt(10)
	s_barrier
	v_bfe_u32 v2, v6, 4, 2
	v_lshlrev_b32_e32 v3, 4, v2
	v_lshlrev_b32_e32 v4, 2, v6
	v_lshl_or_b32 v149, v2, 3, s39
	v_lshlrev_b32_e32 v2, 15, v11
	v_lshl_or_b32 v3, v141, 6, v3
	v_and_b32_e32 v4, 32, v4
	v_and_b32_e32 v2, 0xffff0000, v2
	v_bitop3_b32 v5, v3, s38, v4 bitop3:0xde
	v_bitop3_b32 v143, v3, s40, v4 bitop3:0xde
	v_lshl_add_u32 v2, v10, 12, v2
	v_and_b32_e32 v3, 1, v11
	v_lshl_or_b32 v2, v3, 6, v2
	v_lshl_add_u32 v136, v12, 1, v2
	v_lshlrev_b32_e32 v2, 15, v7
	v_and_b32_e32 v2, 0xffff0000, v2
	v_readlane_b32 s36, v254, 4
	s_waitcnt vmcnt(6)
	v_lshl_add_u32 v2, v8, 12, v2
	v_and_b32_e32 v3, 1, v7
	v_readlane_b32 s37, v254, 5
	v_and_b32_e32 v145, 63, v6
	v_lshl_or_b32 v2, v3, 6, v2
	s_mov_b32 s65, s36
	v_readlane_b32 s36, v254, 2
	v_or_b32_e32 v147, 0x80, v145
	v_mov_b32_e32 v137, v1
	v_lshl_add_u32 v138, v9, 1, v2
	v_mov_b32_e32 v139, v1
	s_mov_b32 s64, 0
	v_add_u32_e32 v151, 0, v5
	s_mov_b32 s68, s36
	s_barrier
	v_readlane_b32 s37, v254, 3

; #define PG8_STAGE(bufoff, gbase, voff) do { _Pragma("unroll") for (int _i = 0; _i < 2; ++_i) \
;         __builtin_amdgcn_global_load_lds((const unsigned*)((const char*)(gbase) + (voff)[_i]), (LAS unsigned*)(lds + (bufoff) + ldsw + _i * 8192), 16, 0, 0); } while (0)
; #define PG8_WAIT_V(n) asm volatile("s_waitcnt vmcnt(" #n ")" ::: "memory")
; #define PG8_BAR __builtin_amdgcn_s_barrier()
; template <class Epi>
; __device__ __forceinline__ void gemm_phase(LAS unsigned char* lds, const Gemm g, const StaticOrder& S, const Epi& E) {
;     ...
;     for (int i = 0; i < 2; ++i) { int R, C; stage_rc(tid * 16 + i * 8192, R, C); const int Rb = (R & ~31) + perm32(R & 31);
;         voffA[i] = (unsigned)(R * K + C) * 2u; voffB[i] = (unsigned)(Rb * K + C) * 2u; }
;     const size_t kstep = (size_t)(BK * 2);
;     const size_t hstep = (size_t)HALF * K * 2;
;     const size_t tstep = 2 * hstep;
;     const unsigned ldsw = (unsigned)wid * 1024u;
;     const int aoff = lds_byte(wr * 64 + fr, fq * 8), boff = lds_byte(wc * 32 + fr, fq * 8);
;     ...
;     PG8_STAGE(PG8_SB(0, 0), cB, voffB); PG8_STAGE(PG8_SA(0, 0), cA, voffA); PG8_STAGE(PG8_SB(0, 1), cB + hstep, voffB); PG8_STAGE(PG8_SA(0, 1), cA + hstep, voffA);
;     if (wr == 1) PG8_BAR;
;     PG8_WAIT_V(4); PG8_BAR;
;     PG8_STAGE(PG8_SB(1, 0), cB + kstep, voffB); PG8_STAGE(PG8_SA(1, 0), cA + kstep, voffA); PG8_STAGE(PG8_SB(1, 1), cB + hstep + kstep, voffB);
;     PG8_WAIT_V(6); PG8_BAR;
.LBB0_641:
	v_readlane_b32 s38, v254, 51
	v_readlane_b32 s39, v254, 52
	s_and_b64 s[38:39], exec, s[38:39]
	v_readlane_b32 s76, v251, 2
	v_readlane_b32 s77, v251, 3
	v_readlane_b32 s38, v251, 56
	s_mov_b64 s[64:65], s[76:77]
	v_readlane_b32 s39, v251, 57
	s_cselect_b32 s55, s65, s39
	s_cselect_b32 s54, s64, s38
	v_bfe_u32 v21, v20, 4, 2
	s_lshl_b32 s2, s2, 5
	v_and_b32_e32 v22, 15, v20
	v_lshlrev_b32_e32 v23, 4, v21
	v_lshlrev_b32_e32 v20, 2, v20
	s_and_b32 s38, s2, 0x60
	s_lshr_b32 s74, s36, 6
	v_lshl_or_b32 v240, s3, 6, v22
	v_lshl_or_b32 v22, v22, 6, v23
	s_lshl_b32 s3, s3, 13
	v_and_b32_e32 v20, 32, v20
	s_lshl_b32 s2, s38, 7
	v_readlane_b32 s36, v254, 38
	v_bitop3_b32 v23, v22, s3, v20 bitop3:0xde
	v_bitop3_b32 v241, v22, s2, v20 bitop3:0xde
	s_lshl_b32 s2, s94, 13
	s_mov_b32 s3, s36
	s_lshl_b64 s[2:3], s[2:3], 2
	v_readlane_b32 s36, v251, 54
	s_add_u32 s56, s36, s2
	v_readlane_b32 s2, v251, 55
	s_addc_u32 s57, s2, s3
	s_add_i32 m0, s70, 0x18000
	v_lshl_add_u64 v[2:3], v[2:3], 0, s[22:23]
	global_load_lds_dwordx4 v[2:3], off
	v_lshl_add_u64 v[2:3], v[4:5], 0, s[22:23]
	s_add_i32 m0, s70, 0x1a000
	s_add_i32 s75, s70, 0x8000
	global_load_lds_dwordx4 v[2:3], off
	v_lshl_add_u64 v[2:3], v[6:7], 0, s[22:23]
	s_mov_b32 m0, s75
	s_add_i32 s76, s70, 0xa000
	global_load_lds_dwordx4 v[2:3], off
	v_lshl_add_u64 v[2:3], v[8:9], 0, s[22:23]
	s_mov_b32 m0, s76
	v_readlane_b32 s78, v251, 4
	global_load_lds_dwordx4 v[2:3], off
	s_add_i32 m0, s70, 0x1c000
	v_lshl_add_u64 v[2:3], v[10:11], 0, s[22:23]
	global_load_lds_dwordx4 v[2:3], off
	v_lshl_add_u64 v[2:3], v[12:13], 0, s[22:23]
	s_add_i32 m0, s70, 0x1e000
	v_readlane_b32 s80, v251, 6
	global_load_lds_dwordx4 v[2:3], off
	s_waitcnt vmcnt(10)
	s_barrier
	v_add_u32_e32 v2, v19, v17
	v_add_lshl_u32 v2, v2, v18, 1
	v_mov_b32_e32 v3, v1
	s_waitcnt vmcnt(6)
	v_lshl_add_u64 v[214:215], s[50:51], 0, v[2:3]
	v_add_u32_e32 v2, v16, v14
	v_readlane_b32 s81, v251, 7
	v_readlane_b32 s37, v254, 39
	v_add_lshl_u32 v2, v2, v15, 1
	v_readlane_b32 s79, v251, 5
	s_add_i32 s77, s74, -2
	s_mov_b32 s78, 0
	v_cmp_eq_u32_e64 s[36:37], 0, v21
	s_mov_b32 s47, s46
	s_mov_b32 s58, s46
	s_mov_b32 s59, s46
	v_lshl_or_b32 v242, v21, 3, s38
	v_lshl_add_u64 v[216:217], s[50:51], 0, v[2:3]
	v_add_u32_e32 v243, 0, v23
	v_readlane_b32 s81, v254, 1
	v_readlane_b32 s80, v253, 63
	v_readlane_b32 s82, v251, 8
	v_readlane_b32 s83, v251, 9
	v_readlane_b32 s84, v251, 10
	v_readlane_b32 s85, v251, 11
	v_readlane_b32 s86, v251, 12
	v_readlane_b32 s87, v251, 13
	v_readlane_b32 s88, v251, 14
	v_readlane_b32 s89, v251, 15
	v_readlane_b32 s90, v251, 16
	v_readlane_b32 s91, v251, 17
	s_barrier
	s_branch .LBB0_643
